# latent WKV: compute waves run at s_setprio 3 inside the chunk body so the loader wave sharing their SIMD does not take their issue slots
# baseline (speedup 1.0000x reference)
.LBB0_185:
	s_and_saveexec_b64 s[20:21], s[40:41]
	s_cbranch_execz .LBB0_194
	s_setprio 3
	ds_read_b128 v[2:5], v228
	ds_read_b128 v[6:9], v228 offset:4096
	ds_read_b128 v[10:13], v228 offset:8192
	ds_read_b128 v[14:17], v228 offset:12288
	ds_read_b128 v[18:21], v228 offset:16384
	ds_read_b32 v22, v229 offset:40960
	ds_read_b128 v[24:27], v228 offset:256
	ds_read_b128 v[28:31], v228 offset:4352
	ds_read_b128 v[32:35], v228 offset:8448
	ds_read_b128 v[36:39], v228 offset:12544
	ds_read_b128 v[40:43], v228 offset:16640
	ds_read_b32 v44, v229 offset:41024
	s_waitcnt vmcnt(0)
	s_waitcnt lgkmcnt(6)
	v_pk_mul_f32 v[80:81], v[52:53], v[8:9]
	v_pk_mul_f32 v[76:77], v[14:15], v[22:23] op_sel_hi:[1,0]
	v_pk_fma_f32 v[80:81], v[50:51], v[6:7], v[80:81]
	v_pk_mul_f32 v[78:79], v[16:17], v[22:23] op_sel_hi:[1,0]
	v_add_f32_e32 v80, v80, v81
	v_pk_fma_f32 v[76:77], v[50:51], v[2:3], v[76:77]
	v_pk_fma_f32 v[78:79], v[52:53], v[4:5], v[78:79]
	v_add_f32_dpp v80, v80, v80 quad_perm:[1,0,3,2] row_mask:0xf bank_mask:0xf bound_ctrl:1
	ds_read_b128 v[54:57], v228 offset:512
	ds_read_b128 v[58:61], v228 offset:4608
	v_add_f32_dpp v80, v80, v80 quad_perm:[2,3,0,1] row_mask:0xf bank_mask:0xf bound_ctrl:1
	ds_read_b128 v[62:65], v228 offset:8704
	ds_read_b128 v[66:69], v228 offset:12800
	v_add_f32_dpp v80, v80, v80 row_half_mirror row_mask:0xf bank_mask:0xf bound_ctrl:1
	ds_read_b128 v[70:73], v228 offset:16896
	ds_read_b32 v74, v229 offset:41088
	v_add_f32_dpp v80, v80, v80 row_mirror row_mask:0xf bank_mask:0xf bound_ctrl:1
	v_pk_fma_f32 v[52:53], v[12:13], v[80:81], v[78:79] op_sel_hi:[1,0,1] neg_lo:[0,1,0] neg_hi:[0,1,0]
	v_pk_fma_f32 v[50:51], v[10:11], v[80:81], v[76:77] op_sel_hi:[1,0,1] neg_lo:[0,1,0] neg_hi:[0,1,0]
	v_pk_mul_f32 v[82:83], v[20:21], v[52:53]
	s_nop 0
	v_pk_fma_f32 v[82:83], v[18:19], v[50:51], v[82:83]
	s_nop 0
	v_add_f32_e32 v82, v82, v83
	ds_write_b32 v244, v82
	s_waitcnt lgkmcnt(7)
	v_pk_mul_f32 v[80:81], v[52:53], v[30:31]
	v_pk_mul_f32 v[76:77], v[36:37], v[44:45] op_sel_hi:[1,0]
	v_pk_fma_f32 v[80:81], v[50:51], v[28:29], v[80:81]
	v_pk_mul_f32 v[78:79], v[38:39], v[44:45] op_sel_hi:[1,0]
	v_add_f32_e32 v80, v80, v81
	v_pk_fma_f32 v[76:77], v[50:51], v[24:25], v[76:77]
	v_pk_fma_f32 v[78:79], v[52:53], v[26:27], v[78:79]
	v_add_f32_dpp v80, v80, v80 quad_perm:[1,0,3,2] row_mask:0xf bank_mask:0xf bound_ctrl:1
	ds_read_b128 v[2:5], v228 offset:768
	ds_read_b128 v[6:9], v228 offset:4864
	v_add_f32_dpp v80, v80, v80 quad_perm:[2,3,0,1] row_mask:0xf bank_mask:0xf bound_ctrl:1
	ds_read_b128 v[10:13], v228 offset:8960
	ds_read_b128 v[14:17], v228 offset:13056
	v_add_f32_dpp v80, v80, v80 row_half_mirror row_mask:0xf bank_mask:0xf bound_ctrl:1
	ds_read_b128 v[18:21], v228 offset:17152
	ds_read_b32 v22, v229 offset:41152
	v_add_f32_dpp v80, v80, v80 row_mirror row_mask:0xf bank_mask:0xf bound_ctrl:1
	v_pk_fma_f32 v[52:53], v[34:35], v[80:81], v[78:79] op_sel_hi:[1,0,1] neg_lo:[0,1,0] neg_hi:[0,1,0]
	v_pk_fma_f32 v[50:51], v[32:33], v[80:81], v[76:77] op_sel_hi:[1,0,1] neg_lo:[0,1,0] neg_hi:[0,1,0]
	v_pk_mul_f32 v[82:83], v[42:43], v[52:53]
	s_nop 0
	v_pk_fma_f32 v[82:83], v[40:41], v[50:51], v[82:83]
	s_nop 0
	v_add_f32_e32 v82, v82, v83
	ds_write_b32 v244, v82 offset:256
	s_waitcnt lgkmcnt(8)
	v_pk_mul_f32 v[80:81], v[52:53], v[60:61]
	v_pk_mul_f32 v[76:77], v[66:67], v[74:75] op_sel_hi:[1,0]
	v_pk_fma_f32 v[80:81], v[50:51], v[58:59], v[80:81]
	v_pk_mul_f32 v[78:79], v[68:69], v[74:75] op_sel_hi:[1,0]
	v_add_f32_e32 v80, v80, v81
	v_pk_fma_f32 v[76:77], v[50:51], v[54:55], v[76:77]
	v_pk_fma_f32 v[78:79], v[52:53], v[56:57], v[78:79]
	v_add_f32_dpp v80, v80, v80 quad_perm:[1,0,3,2] row_mask:0xf bank_mask:0xf bound_ctrl:1
	ds_read_b128 v[24:27], v228 offset:1024
	ds_read_b128 v[28:31], v228 offset:5120
	v_add_f32_dpp v80, v80, v80 quad_perm:[2,3,0,1] row_mask:0xf bank_mask:0xf bound_ctrl:1
	ds_read_b128 v[32:35], v228 offset:9216
	ds_read_b128 v[36:39], v228 offset:13312
	v_add_f32_dpp v80, v80, v80 row_half_mirror row_mask:0xf bank_mask:0xf bound_ctrl:1
	ds_read_b128 v[40:43], v228 offset:17408
	ds_read_b32 v44, v229 offset:41216
	v_add_f32_dpp v80, v80, v80 row_mirror row_mask:0xf bank_mask:0xf bound_ctrl:1
	v_pk_fma_f32 v[52:53], v[64:65], v[80:81], v[78:79] op_sel_hi:[1,0,1] neg_lo:[0,1,0] neg_hi:[0,1,0]
	v_pk_fma_f32 v[50:51], v[62:63], v[80:81], v[76:77] op_sel_hi:[1,0,1] neg_lo:[0,1,0] neg_hi:[0,1,0]
	v_pk_mul_f32 v[82:83], v[72:73], v[52:53]
	s_nop 0
	v_pk_fma_f32 v[82:83], v[70:71], v[50:51], v[82:83]
	s_nop 0
	v_add_f32_e32 v82, v82, v83
	ds_write_b32 v244, v82 offset:512
	s_waitcnt lgkmcnt(8)
	v_pk_mul_f32 v[80:81], v[52:53], v[8:9]
	v_pk_mul_f32 v[76:77], v[14:15], v[22:23] op_sel_hi:[1,0]
	v_pk_fma_f32 v[80:81], v[50:51], v[6:7], v[80:81]
	v_pk_mul_f32 v[78:79], v[16:17], v[22:23] op_sel_hi:[1,0]
	v_add_f32_e32 v80, v80, v81
	v_pk_fma_f32 v[76:77], v[50:51], v[2:3], v[76:77]
	v_pk_fma_f32 v[78:79], v[52:53], v[4:5], v[78:79]
	v_add_f32_dpp v80, v80, v80 quad_perm:[1,0,3,2] row_mask:0xf bank_mask:0xf bound_ctrl:1
	ds_read_b128 v[54:57], v228 offset:1280
	ds_read_b128 v[58:61], v228 offset:5376
	v_add_f32_dpp v80, v80, v80 quad_perm:[2,3,0,1] row_mask:0xf bank_mask:0xf bound_ctrl:1
	ds_read_b128 v[62:65], v228 offset:9472
	ds_read_b128 v[66:69], v228 offset:13568
	v_add_f32_dpp v80, v80, v80 row_half_mirror row_mask:0xf bank_mask:0xf bound_ctrl:1
	ds_read_b128 v[70:73], v228 offset:17664
	ds_read_b32 v74, v229 offset:41280
	v_add_f32_dpp v80, v80, v80 row_mirror row_mask:0xf bank_mask:0xf bound_ctrl:1
	v_pk_fma_f32 v[52:53], v[12:13], v[80:81], v[78:79] op_sel_hi:[1,0,1] neg_lo:[0,1,0] neg_hi:[0,1,0]
	v_pk_fma_f32 v[50:51], v[10:11], v[80:81], v[76:77] op_sel_hi:[1,0,1] neg_lo:[0,1,0] neg_hi:[0,1,0]
	v_pk_mul_f32 v[82:83], v[20:21], v[52:53]
	s_nop 0
	v_pk_fma_f32 v[82:83], v[18:19], v[50:51], v[82:83]
	s_nop 0
	v_add_f32_e32 v82, v82, v83
	ds_write_b32 v244, v82 offset:768
	s_waitcnt lgkmcnt(8)
	v_pk_mul_f32 v[80:81], v[52:53], v[30:31]
	v_pk_mul_f32 v[76:77], v[36:37], v[44:45] op_sel_hi:[1,0]
	v_pk_fma_f32 v[80:81], v[50:51], v[28:29], v[80:81]
	v_pk_mul_f32 v[78:79], v[38:39], v[44:45] op_sel_hi:[1,0]
	v_add_f32_e32 v80, v80, v81
	v_pk_fma_f32 v[76:77], v[50:51], v[24:25], v[76:77]
	v_pk_fma_f32 v[78:79], v[52:53], v[26:27], v[78:79]
	v_add_f32_dpp v80, v80, v80 quad_perm:[1,0,3,2] row_mask:0xf bank_mask:0xf bound_ctrl:1
	ds_read_b128 v[2:5], v228 offset:1536
	ds_read_b128 v[6:9], v228 offset:5632
	v_add_f32_dpp v80, v80, v80 quad_perm:[2,3,0,1] row_mask:0xf bank_mask:0xf bound_ctrl:1
	ds_read_b128 v[10:13], v228 offset:9728
	ds_read_b128 v[14:17], v228 offset:13824
	v_add_f32_dpp v80, v80, v80 row_half_mirror row_mask:0xf bank_mask:0xf bound_ctrl:1
	ds_read_b128 v[18:21], v228 offset:17920
	ds_read_b32 v22, v229 offset:41344
	v_add_f32_dpp v80, v80, v80 row_mirror row_mask:0xf bank_mask:0xf bound_ctrl:1
	v_pk_fma_f32 v[52:53], v[34:35], v[80:81], v[78:79] op_sel_hi:[1,0,1] neg_lo:[0,1,0] neg_hi:[0,1,0]
	v_pk_fma_f32 v[50:51], v[32:33], v[80:81], v[76:77] op_sel_hi:[1,0,1] neg_lo:[0,1,0] neg_hi:[0,1,0]
	v_pk_mul_f32 v[82:83], v[42:43], v[52:53]
	s_nop 0
	v_pk_fma_f32 v[82:83], v[40:41], v[50:51], v[82:83]
	s_nop 0
	v_add_f32_e32 v82, v82, v83
	ds_write_b32 v244, v82 offset:1024
	s_waitcnt lgkmcnt(8)
	v_pk_mul_f32 v[80:81], v[52:53], v[60:61]
	v_pk_mul_f32 v[76:77], v[66:67], v[74:75] op_sel_hi:[1,0]
	v_pk_fma_f32 v[80:81], v[50:51], v[58:59], v[80:81]
	v_pk_mul_f32 v[78:79], v[68:69], v[74:75] op_sel_hi:[1,0]
	v_add_f32_e32 v80, v80, v81
	v_pk_fma_f32 v[76:77], v[50:51], v[54:55], v[76:77]
	v_pk_fma_f32 v[78:79], v[52:53], v[56:57], v[78:79]
	v_add_f32_dpp v80, v80, v80 quad_perm:[1,0,3,2] row_mask:0xf bank_mask:0xf bound_ctrl:1
	ds_read_b128 v[24:27], v228 offset:1792
	ds_read_b128 v[28:31], v228 offset:5888
	v_add_f32_dpp v80, v80, v80 quad_perm:[2,3,0,1] row_mask:0xf bank_mask:0xf bound_ctrl:1
	ds_read_b128 v[32:35], v228 offset:9984
	ds_read_b128 v[36:39], v228 offset:14080
	v_add_f32_dpp v80, v80, v80 row_half_mirror row_mask:0xf bank_mask:0xf bound_ctrl:1
	ds_read_b128 v[40:43], v228 offset:18176
	ds_read_b32 v44, v229 offset:41408
	v_add_f32_dpp v80, v80, v80 row_mirror row_mask:0xf bank_mask:0xf bound_ctrl:1
	v_pk_fma_f32 v[52:53], v[64:65], v[80:81], v[78:79] op_sel_hi:[1,0,1] neg_lo:[0,1,0] neg_hi:[0,1,0]
	v_pk_fma_f32 v[50:51], v[62:63], v[80:81], v[76:77] op_sel_hi:[1,0,1] neg_lo:[0,1,0] neg_hi:[0,1,0]
	v_pk_mul_f32 v[82:83], v[72:73], v[52:53]
	s_nop 0
	v_pk_fma_f32 v[82:83], v[70:71], v[50:51], v[82:83]
	s_nop 0
	v_add_f32_e32 v82, v82, v83
	ds_write_b32 v244, v82 offset:1280
	s_waitcnt lgkmcnt(8)
	v_pk_mul_f32 v[80:81], v[52:53], v[8:9]
	v_pk_mul_f32 v[76:77], v[14:15], v[22:23] op_sel_hi:[1,0]
	v_pk_fma_f32 v[80:81], v[50:51], v[6:7], v[80:81]
	v_pk_mul_f32 v[78:79], v[16:17], v[22:23] op_sel_hi:[1,0]
	v_add_f32_e32 v80, v80, v81
	v_pk_fma_f32 v[76:77], v[50:51], v[2:3], v[76:77]
	v_pk_fma_f32 v[78:79], v[52:53], v[4:5], v[78:79]
	v_add_f32_dpp v80, v80, v80 quad_perm:[1,0,3,2] row_mask:0xf bank_mask:0xf bound_ctrl:1
	ds_read_b128 v[54:57], v228 offset:2048
	ds_read_b128 v[58:61], v228 offset:6144
	v_add_f32_dpp v80, v80, v80 quad_perm:[2,3,0,1] row_mask:0xf bank_mask:0xf bound_ctrl:1
	ds_read_b128 v[62:65], v228 offset:10240
	ds_read_b128 v[66:69], v228 offset:14336
	v_add_f32_dpp v80, v80, v80 row_half_mirror row_mask:0xf bank_mask:0xf bound_ctrl:1
	ds_read_b128 v[70:73], v228 offset:18432
	ds_read_b32 v74, v229 offset:41472
	v_add_f32_dpp v80, v80, v80 row_mirror row_mask:0xf bank_mask:0xf bound_ctrl:1
	v_pk_fma_f32 v[52:53], v[12:13], v[80:81], v[78:79] op_sel_hi:[1,0,1] neg_lo:[0,1,0] neg_hi:[0,1,0]
	v_pk_fma_f32 v[50:51], v[10:11], v[80:81], v[76:77] op_sel_hi:[1,0,1] neg_lo:[0,1,0] neg_hi:[0,1,0]
	v_pk_mul_f32 v[82:83], v[20:21], v[52:53]
	s_nop 0
	v_pk_fma_f32 v[82:83], v[18:19], v[50:51], v[82:83]
	s_nop 0
	v_add_f32_e32 v82, v82, v83
	ds_write_b32 v244, v82 offset:1536
	s_waitcnt lgkmcnt(8)
	v_pk_mul_f32 v[80:81], v[52:53], v[30:31]
	v_pk_mul_f32 v[76:77], v[36:37], v[44:45] op_sel_hi:[1,0]
	v_pk_fma_f32 v[80:81], v[50:51], v[28:29], v[80:81]
	v_pk_mul_f32 v[78:79], v[38:39], v[44:45] op_sel_hi:[1,0]
	v_add_f32_e32 v80, v80, v81
	v_pk_fma_f32 v[76:77], v[50:51], v[24:25], v[76:77]
	v_pk_fma_f32 v[78:79], v[52:53], v[26:27], v[78:79]
	v_add_f32_dpp v80, v80, v80 quad_perm:[1,0,3,2] row_mask:0xf bank_mask:0xf bound_ctrl:1
	ds_read_b128 v[2:5], v228 offset:2304
	ds_read_b128 v[6:9], v228 offset:6400
	v_add_f32_dpp v80, v80, v80 quad_perm:[2,3,0,1] row_mask:0xf bank_mask:0xf bound_ctrl:1
	ds_read_b128 v[10:13], v228 offset:10496
	ds_read_b128 v[14:17], v228 offset:14592
	v_add_f32_dpp v80, v80, v80 row_half_mirror row_mask:0xf bank_mask:0xf bound_ctrl:1
	ds_read_b128 v[18:21], v228 offset:18688
	ds_read_b32 v22, v229 offset:41536
	v_add_f32_dpp v80, v80, v80 row_mirror row_mask:0xf bank_mask:0xf bound_ctrl:1
	v_pk_fma_f32 v[52:53], v[34:35], v[80:81], v[78:79] op_sel_hi:[1,0,1] neg_lo:[0,1,0] neg_hi:[0,1,0]
	v_pk_fma_f32 v[50:51], v[32:33], v[80:81], v[76:77] op_sel_hi:[1,0,1] neg_lo:[0,1,0] neg_hi:[0,1,0]
	v_pk_mul_f32 v[82:83], v[42:43], v[52:53]
	s_nop 0
	v_pk_fma_f32 v[82:83], v[40:41], v[50:51], v[82:83]
	s_nop 0
	v_add_f32_e32 v82, v82, v83
	ds_write_b32 v244, v82 offset:1792
	s_waitcnt lgkmcnt(8)
	v_pk_mul_f32 v[80:81], v[52:53], v[60:61]
	v_pk_mul_f32 v[76:77], v[66:67], v[74:75] op_sel_hi:[1,0]
	v_pk_fma_f32 v[80:81], v[50:51], v[58:59], v[80:81]
	v_pk_mul_f32 v[78:79], v[68:69], v[74:75] op_sel_hi:[1,0]
	v_add_f32_e32 v80, v80, v81
	v_pk_fma_f32 v[76:77], v[50:51], v[54:55], v[76:77]
	v_pk_fma_f32 v[78:79], v[52:53], v[56:57], v[78:79]
	v_add_f32_dpp v80, v80, v80 quad_perm:[1,0,3,2] row_mask:0xf bank_mask:0xf bound_ctrl:1
	ds_read_b128 v[24:27], v228 offset:2560
	ds_read_b128 v[28:31], v228 offset:6656
	v_add_f32_dpp v80, v80, v80 quad_perm:[2,3,0,1] row_mask:0xf bank_mask:0xf bound_ctrl:1
	ds_read_b128 v[32:35], v228 offset:10752
	ds_read_b128 v[36:39], v228 offset:14848
	v_add_f32_dpp v80, v80, v80 row_half_mirror row_mask:0xf bank_mask:0xf bound_ctrl:1
	ds_read_b128 v[40:43], v228 offset:18944
	ds_read_b32 v44, v229 offset:41600
	v_add_f32_dpp v80, v80, v80 row_mirror row_mask:0xf bank_mask:0xf bound_ctrl:1
	v_pk_fma_f32 v[52:53], v[64:65], v[80:81], v[78:79] op_sel_hi:[1,0,1] neg_lo:[0,1,0] neg_hi:[0,1,0]
	v_pk_fma_f32 v[50:51], v[62:63], v[80:81], v[76:77] op_sel_hi:[1,0,1] neg_lo:[0,1,0] neg_hi:[0,1,0]
	v_pk_mul_f32 v[82:83], v[72:73], v[52:53]
	s_nop 0
	v_pk_fma_f32 v[82:83], v[70:71], v[50:51], v[82:83]
	s_nop 0
	v_add_f32_e32 v82, v82, v83
	ds_write_b32 v244, v82 offset:2048
	s_waitcnt lgkmcnt(8)
	v_pk_mul_f32 v[80:81], v[52:53], v[8:9]
	v_pk_mul_f32 v[76:77], v[14:15], v[22:23] op_sel_hi:[1,0]
	v_pk_fma_f32 v[80:81], v[50:51], v[6:7], v[80:81]
	v_pk_mul_f32 v[78:79], v[16:17], v[22:23] op_sel_hi:[1,0]
	v_add_f32_e32 v80, v80, v81
	v_pk_fma_f32 v[76:77], v[50:51], v[2:3], v[76:77]
	v_pk_fma_f32 v[78:79], v[52:53], v[4:5], v[78:79]
	v_add_f32_dpp v80, v80, v80 quad_perm:[1,0,3,2] row_mask:0xf bank_mask:0xf bound_ctrl:1
	ds_read_b128 v[54:57], v228 offset:2816
	ds_read_b128 v[58:61], v228 offset:6912
	v_add_f32_dpp v80, v80, v80 quad_perm:[2,3,0,1] row_mask:0xf bank_mask:0xf bound_ctrl:1
	ds_read_b128 v[62:65], v228 offset:11008
	ds_read_b128 v[66:69], v228 offset:15104
	v_add_f32_dpp v80, v80, v80 row_half_mirror row_mask:0xf bank_mask:0xf bound_ctrl:1
	ds_read_b128 v[70:73], v228 offset:19200
	ds_read_b32 v74, v229 offset:41664
	v_add_f32_dpp v80, v80, v80 row_mirror row_mask:0xf bank_mask:0xf bound_ctrl:1
	v_pk_fma_f32 v[52:53], v[12:13], v[80:81], v[78:79] op_sel_hi:[1,0,1] neg_lo:[0,1,0] neg_hi:[0,1,0]
	v_pk_fma_f32 v[50:51], v[10:11], v[80:81], v[76:77] op_sel_hi:[1,0,1] neg_lo:[0,1,0] neg_hi:[0,1,0]
	v_pk_mul_f32 v[82:83], v[20:21], v[52:53]
	s_nop 0
	v_pk_fma_f32 v[82:83], v[18:19], v[50:51], v[82:83]
	s_nop 0
	v_add_f32_e32 v82, v82, v83
	ds_write_b32 v244, v82 offset:2304
	s_waitcnt lgkmcnt(8)
	v_pk_mul_f32 v[80:81], v[52:53], v[30:31]
	v_pk_mul_f32 v[76:77], v[36:37], v[44:45] op_sel_hi:[1,0]
	v_pk_fma_f32 v[80:81], v[50:51], v[28:29], v[80:81]
	v_pk_mul_f32 v[78:79], v[38:39], v[44:45] op_sel_hi:[1,0]
	v_add_f32_e32 v80, v80, v81
	v_pk_fma_f32 v[76:77], v[50:51], v[24:25], v[76:77]
	v_pk_fma_f32 v[78:79], v[52:53], v[26:27], v[78:79]
	v_add_f32_dpp v80, v80, v80 quad_perm:[1,0,3,2] row_mask:0xf bank_mask:0xf bound_ctrl:1
	ds_read_b128 v[2:5], v228 offset:3072
	ds_read_b128 v[6:9], v228 offset:7168
	v_add_f32_dpp v80, v80, v80 quad_perm:[2,3,0,1] row_mask:0xf bank_mask:0xf bound_ctrl:1
	ds_read_b128 v[10:13], v228 offset:11264
	ds_read_b128 v[14:17], v228 offset:15360
	v_add_f32_dpp v80, v80, v80 row_half_mirror row_mask:0xf bank_mask:0xf bound_ctrl:1
	ds_read_b128 v[18:21], v228 offset:19456
	ds_read_b32 v22, v229 offset:41728
	v_add_f32_dpp v80, v80, v80 row_mirror row_mask:0xf bank_mask:0xf bound_ctrl:1
	v_pk_fma_f32 v[52:53], v[34:35], v[80:81], v[78:79] op_sel_hi:[1,0,1] neg_lo:[0,1,0] neg_hi:[0,1,0]
	v_pk_fma_f32 v[50:51], v[32:33], v[80:81], v[76:77] op_sel_hi:[1,0,1] neg_lo:[0,1,0] neg_hi:[0,1,0]
	v_pk_mul_f32 v[82:83], v[42:43], v[52:53]
	s_nop 0
	v_pk_fma_f32 v[82:83], v[40:41], v[50:51], v[82:83]
	s_nop 0
	v_add_f32_e32 v82, v82, v83
	ds_write_b32 v244, v82 offset:2560
	s_waitcnt lgkmcnt(8)
	v_pk_mul_f32 v[80:81], v[52:53], v[60:61]
	v_pk_mul_f32 v[76:77], v[66:67], v[74:75] op_sel_hi:[1,0]
	v_pk_fma_f32 v[80:81], v[50:51], v[58:59], v[80:81]
	v_pk_mul_f32 v[78:79], v[68:69], v[74:75] op_sel_hi:[1,0]
	v_add_f32_e32 v80, v80, v81
	v_pk_fma_f32 v[76:77], v[50:51], v[54:55], v[76:77]
	v_pk_fma_f32 v[78:79], v[52:53], v[56:57], v[78:79]
	v_add_f32_dpp v80, v80, v80 quad_perm:[1,0,3,2] row_mask:0xf bank_mask:0xf bound_ctrl:1
	ds_read_b128 v[24:27], v228 offset:3328
	ds_read_b128 v[28:31], v228 offset:7424
	v_add_f32_dpp v80, v80, v80 quad_perm:[2,3,0,1] row_mask:0xf bank_mask:0xf bound_ctrl:1
	ds_read_b128 v[32:35], v228 offset:11520
	ds_read_b128 v[36:39], v228 offset:15616
	v_add_f32_dpp v80, v80, v80 row_half_mirror row_mask:0xf bank_mask:0xf bound_ctrl:1
	ds_read_b128 v[40:43], v228 offset:19712
	ds_read_b32 v44, v229 offset:41792
	v_add_f32_dpp v80, v80, v80 row_mirror row_mask:0xf bank_mask:0xf bound_ctrl:1
	v_pk_fma_f32 v[52:53], v[64:65], v[80:81], v[78:79] op_sel_hi:[1,0,1] neg_lo:[0,1,0] neg_hi:[0,1,0]
	v_pk_fma_f32 v[50:51], v[62:63], v[80:81], v[76:77] op_sel_hi:[1,0,1] neg_lo:[0,1,0] neg_hi:[0,1,0]
	v_pk_mul_f32 v[82:83], v[72:73], v[52:53]
	s_nop 0
	v_pk_fma_f32 v[82:83], v[70:71], v[50:51], v[82:83]
	s_nop 0
	v_add_f32_e32 v82, v82, v83
	ds_write_b32 v244, v82 offset:2816
	s_waitcnt lgkmcnt(8)
	v_pk_mul_f32 v[80:81], v[52:53], v[8:9]
	v_pk_mul_f32 v[76:77], v[14:15], v[22:23] op_sel_hi:[1,0]
	v_pk_fma_f32 v[80:81], v[50:51], v[6:7], v[80:81]
	v_pk_mul_f32 v[78:79], v[16:17], v[22:23] op_sel_hi:[1,0]
	v_add_f32_e32 v80, v80, v81
	v_pk_fma_f32 v[76:77], v[50:51], v[2:3], v[76:77]
	v_pk_fma_f32 v[78:79], v[52:53], v[4:5], v[78:79]
	v_add_f32_dpp v80, v80, v80 quad_perm:[1,0,3,2] row_mask:0xf bank_mask:0xf bound_ctrl:1
	ds_read_b128 v[54:57], v228 offset:3584
	ds_read_b128 v[58:61], v228 offset:7680
	v_add_f32_dpp v80, v80, v80 quad_perm:[2,3,0,1] row_mask:0xf bank_mask:0xf bound_ctrl:1
	ds_read_b128 v[62:65], v228 offset:11776
	ds_read_b128 v[66:69], v228 offset:15872
	v_add_f32_dpp v80, v80, v80 row_half_mirror row_mask:0xf bank_mask:0xf bound_ctrl:1
	ds_read_b128 v[70:73], v228 offset:19968
	ds_read_b32 v74, v229 offset:41856
	v_add_f32_dpp v80, v80, v80 row_mirror row_mask:0xf bank_mask:0xf bound_ctrl:1
	v_pk_fma_f32 v[52:53], v[12:13], v[80:81], v[78:79] op_sel_hi:[1,0,1] neg_lo:[0,1,0] neg_hi:[0,1,0]
	v_pk_fma_f32 v[50:51], v[10:11], v[80:81], v[76:77] op_sel_hi:[1,0,1] neg_lo:[0,1,0] neg_hi:[0,1,0]
	v_pk_mul_f32 v[82:83], v[20:21], v[52:53]
	s_nop 0
	v_pk_fma_f32 v[82:83], v[18:19], v[50:51], v[82:83]
	s_nop 0
	v_add_f32_e32 v82, v82, v83
	ds_write_b32 v244, v82 offset:3072
	s_waitcnt lgkmcnt(8)
	v_pk_mul_f32 v[80:81], v[52:53], v[30:31]
	v_pk_mul_f32 v[76:77], v[36:37], v[44:45] op_sel_hi:[1,0]
	v_pk_fma_f32 v[80:81], v[50:51], v[28:29], v[80:81]
	v_pk_mul_f32 v[78:79], v[38:39], v[44:45] op_sel_hi:[1,0]
	v_add_f32_e32 v80, v80, v81
	v_pk_fma_f32 v[76:77], v[50:51], v[24:25], v[76:77]
	v_pk_fma_f32 v[78:79], v[52:53], v[26:27], v[78:79]
	v_add_f32_dpp v80, v80, v80 quad_perm:[1,0,3,2] row_mask:0xf bank_mask:0xf bound_ctrl:1
	ds_read_b128 v[2:5], v228 offset:3840
	ds_read_b128 v[6:9], v228 offset:7936
	v_add_f32_dpp v80, v80, v80 quad_perm:[2,3,0,1] row_mask:0xf bank_mask:0xf bound_ctrl:1
	ds_read_b128 v[10:13], v228 offset:12032
	ds_read_b128 v[14:17], v228 offset:16128
	v_add_f32_dpp v80, v80, v80 row_half_mirror row_mask:0xf bank_mask:0xf bound_ctrl:1
	ds_read_b128 v[18:21], v228 offset:20224
	ds_read_b32 v22, v229 offset:41920
	v_add_f32_dpp v80, v80, v80 row_mirror row_mask:0xf bank_mask:0xf bound_ctrl:1
	v_pk_fma_f32 v[52:53], v[34:35], v[80:81], v[78:79] op_sel_hi:[1,0,1] neg_lo:[0,1,0] neg_hi:[0,1,0]
	v_pk_fma_f32 v[50:51], v[32:33], v[80:81], v[76:77] op_sel_hi:[1,0,1] neg_lo:[0,1,0] neg_hi:[0,1,0]
	v_pk_mul_f32 v[82:83], v[42:43], v[52:53]
	s_nop 0
	v_pk_fma_f32 v[82:83], v[40:41], v[50:51], v[82:83]
	s_nop 0
	v_add_f32_e32 v82, v82, v83
	ds_write_b32 v244, v82 offset:3328
	s_waitcnt lgkmcnt(8)
	v_pk_mul_f32 v[80:81], v[52:53], v[60:61]
	v_pk_mul_f32 v[76:77], v[66:67], v[74:75] op_sel_hi:[1,0]
	v_pk_fma_f32 v[80:81], v[50:51], v[58:59], v[80:81]
	v_pk_mul_f32 v[78:79], v[68:69], v[74:75] op_sel_hi:[1,0]
	v_add_f32_e32 v80, v80, v81
	v_pk_fma_f32 v[76:77], v[50:51], v[54:55], v[76:77]
	v_pk_fma_f32 v[78:79], v[52:53], v[56:57], v[78:79]
	v_add_f32_dpp v80, v80, v80 quad_perm:[1,0,3,2] row_mask:0xf bank_mask:0xf bound_ctrl:1
	s_nop 1
	v_add_f32_dpp v80, v80, v80 quad_perm:[2,3,0,1] row_mask:0xf bank_mask:0xf bound_ctrl:1
	s_nop 1
	v_add_f32_dpp v80, v80, v80 row_half_mirror row_mask:0xf bank_mask:0xf bound_ctrl:1
	s_nop 1
	v_add_f32_dpp v80, v80, v80 row_mirror row_mask:0xf bank_mask:0xf bound_ctrl:1
	v_pk_fma_f32 v[52:53], v[64:65], v[80:81], v[78:79] op_sel_hi:[1,0,1] neg_lo:[0,1,0] neg_hi:[0,1,0]
	v_pk_fma_f32 v[50:51], v[62:63], v[80:81], v[76:77] op_sel_hi:[1,0,1] neg_lo:[0,1,0] neg_hi:[0,1,0]
	v_pk_mul_f32 v[82:83], v[72:73], v[52:53]
	s_nop 0
	v_pk_fma_f32 v[82:83], v[70:71], v[50:51], v[82:83]
	s_nop 0
	v_add_f32_e32 v82, v82, v83
	ds_write_b32 v244, v82 offset:3584
	s_waitcnt lgkmcnt(2)
	v_pk_mul_f32 v[80:81], v[52:53], v[8:9]
	v_pk_mul_f32 v[76:77], v[14:15], v[22:23] op_sel_hi:[1,0]
	v_pk_fma_f32 v[80:81], v[50:51], v[6:7], v[80:81]
	v_pk_mul_f32 v[78:79], v[16:17], v[22:23] op_sel_hi:[1,0]
	v_add_f32_e32 v80, v80, v81
	v_pk_fma_f32 v[76:77], v[50:51], v[2:3], v[76:77]
	v_pk_fma_f32 v[78:79], v[52:53], v[4:5], v[78:79]
	v_add_f32_dpp v80, v80, v80 quad_perm:[1,0,3,2] row_mask:0xf bank_mask:0xf bound_ctrl:1
	s_nop 1
	v_add_f32_dpp v80, v80, v80 quad_perm:[2,3,0,1] row_mask:0xf bank_mask:0xf bound_ctrl:1
	s_nop 1
	v_add_f32_dpp v80, v80, v80 row_half_mirror row_mask:0xf bank_mask:0xf bound_ctrl:1
	s_nop 1
	v_add_f32_dpp v80, v80, v80 row_mirror row_mask:0xf bank_mask:0xf bound_ctrl:1
	v_pk_fma_f32 v[52:53], v[12:13], v[80:81], v[78:79] op_sel_hi:[1,0,1] neg_lo:[0,1,0] neg_hi:[0,1,0]
	v_pk_fma_f32 v[50:51], v[10:11], v[80:81], v[76:77] op_sel_hi:[1,0,1] neg_lo:[0,1,0] neg_hi:[0,1,0]
	v_pk_mul_f32 v[82:83], v[20:21], v[52:53]
	s_nop 0
	v_pk_fma_f32 v[82:83], v[18:19], v[50:51], v[82:83]
	s_nop 0
	v_add_f32_e32 v82, v82, v83
	ds_write_b32 v244, v82 offset:3840
	s_setprio 0

.LBB0_202:
	s_or_b64 exec, exec, s[20:21]
	s_or_b32 s28, s79, 1
	s_waitcnt lgkmcnt(0)
	s_barrier
	s_and_saveexec_b64 s[20:21], s[40:41]
	s_cbranch_execz .LBB0_211
	s_setprio 3
	ds_read_b128 v[2:5], v228 offset:20480
	ds_read_b128 v[6:9], v228 offset:24576
	ds_read_b128 v[10:13], v228 offset:28672
	ds_read_b128 v[14:17], v228 offset:32768
	ds_read_b128 v[18:21], v228 offset:36864
	ds_read_b32 v22, v229 offset:41984
	ds_read_b128 v[24:27], v228 offset:20736
	ds_read_b128 v[28:31], v228 offset:24832
	ds_read_b128 v[32:35], v228 offset:28928
	ds_read_b128 v[36:39], v228 offset:33024
	ds_read_b128 v[40:43], v228 offset:37120
	ds_read_b32 v44, v229 offset:42048
	s_waitcnt vmcnt(0)
	s_waitcnt lgkmcnt(6)
	v_pk_mul_f32 v[80:81], v[52:53], v[8:9]
	v_pk_mul_f32 v[76:77], v[14:15], v[22:23] op_sel_hi:[1,0]
	v_pk_fma_f32 v[80:81], v[50:51], v[6:7], v[80:81]
	v_pk_mul_f32 v[78:79], v[16:17], v[22:23] op_sel_hi:[1,0]
	v_add_f32_e32 v80, v80, v81
	v_pk_fma_f32 v[76:77], v[50:51], v[2:3], v[76:77]
	v_pk_fma_f32 v[78:79], v[52:53], v[4:5], v[78:79]
	v_add_f32_dpp v80, v80, v80 quad_perm:[1,0,3,2] row_mask:0xf bank_mask:0xf bound_ctrl:1
	ds_read_b128 v[54:57], v228 offset:20992
	ds_read_b128 v[58:61], v228 offset:25088
	v_add_f32_dpp v80, v80, v80 quad_perm:[2,3,0,1] row_mask:0xf bank_mask:0xf bound_ctrl:1
	ds_read_b128 v[62:65], v228 offset:29184
	ds_read_b128 v[66:69], v228 offset:33280
	v_add_f32_dpp v80, v80, v80 row_half_mirror row_mask:0xf bank_mask:0xf bound_ctrl:1
	ds_read_b128 v[70:73], v228 offset:37376
	ds_read_b32 v74, v229 offset:42112
	v_add_f32_dpp v80, v80, v80 row_mirror row_mask:0xf bank_mask:0xf bound_ctrl:1
	v_pk_fma_f32 v[52:53], v[12:13], v[80:81], v[78:79] op_sel_hi:[1,0,1] neg_lo:[0,1,0] neg_hi:[0,1,0]
	v_pk_fma_f32 v[50:51], v[10:11], v[80:81], v[76:77] op_sel_hi:[1,0,1] neg_lo:[0,1,0] neg_hi:[0,1,0]
	v_pk_mul_f32 v[82:83], v[20:21], v[52:53]
	s_nop 0
	v_pk_fma_f32 v[82:83], v[18:19], v[50:51], v[82:83]
	s_nop 0
	v_add_f32_e32 v82, v82, v83
	ds_write_b32 v246, v82
	s_waitcnt lgkmcnt(7)
	v_pk_mul_f32 v[80:81], v[52:53], v[30:31]
	v_pk_mul_f32 v[76:77], v[36:37], v[44:45] op_sel_hi:[1,0]
	v_pk_fma_f32 v[80:81], v[50:51], v[28:29], v[80:81]
	v_pk_mul_f32 v[78:79], v[38:39], v[44:45] op_sel_hi:[1,0]
	v_add_f32_e32 v80, v80, v81
	v_pk_fma_f32 v[76:77], v[50:51], v[24:25], v[76:77]
	v_pk_fma_f32 v[78:79], v[52:53], v[26:27], v[78:79]
	v_add_f32_dpp v80, v80, v80 quad_perm:[1,0,3,2] row_mask:0xf bank_mask:0xf bound_ctrl:1
	ds_read_b128 v[2:5], v228 offset:21248
	ds_read_b128 v[6:9], v228 offset:25344
	v_add_f32_dpp v80, v80, v80 quad_perm:[2,3,0,1] row_mask:0xf bank_mask:0xf bound_ctrl:1
	ds_read_b128 v[10:13], v228 offset:29440
	ds_read_b128 v[14:17], v228 offset:33536
	v_add_f32_dpp v80, v80, v80 row_half_mirror row_mask:0xf bank_mask:0xf bound_ctrl:1
	ds_read_b128 v[18:21], v228 offset:37632
	ds_read_b32 v22, v229 offset:42176
	v_add_f32_dpp v80, v80, v80 row_mirror row_mask:0xf bank_mask:0xf bound_ctrl:1
	v_pk_fma_f32 v[52:53], v[34:35], v[80:81], v[78:79] op_sel_hi:[1,0,1] neg_lo:[0,1,0] neg_hi:[0,1,0]
	v_pk_fma_f32 v[50:51], v[32:33], v[80:81], v[76:77] op_sel_hi:[1,0,1] neg_lo:[0,1,0] neg_hi:[0,1,0]
	v_pk_mul_f32 v[82:83], v[42:43], v[52:53]
	s_nop 0
	v_pk_fma_f32 v[82:83], v[40:41], v[50:51], v[82:83]
	s_nop 0
	v_add_f32_e32 v82, v82, v83
	ds_write_b32 v246, v82 offset:256
	s_waitcnt lgkmcnt(8)
	v_pk_mul_f32 v[80:81], v[52:53], v[60:61]
	v_pk_mul_f32 v[76:77], v[66:67], v[74:75] op_sel_hi:[1,0]
	v_pk_fma_f32 v[80:81], v[50:51], v[58:59], v[80:81]
	v_pk_mul_f32 v[78:79], v[68:69], v[74:75] op_sel_hi:[1,0]
	v_add_f32_e32 v80, v80, v81
	v_pk_fma_f32 v[76:77], v[50:51], v[54:55], v[76:77]
	v_pk_fma_f32 v[78:79], v[52:53], v[56:57], v[78:79]
	v_add_f32_dpp v80, v80, v80 quad_perm:[1,0,3,2] row_mask:0xf bank_mask:0xf bound_ctrl:1
	ds_read_b128 v[24:27], v228 offset:21504
	ds_read_b128 v[28:31], v228 offset:25600
	v_add_f32_dpp v80, v80, v80 quad_perm:[2,3,0,1] row_mask:0xf bank_mask:0xf bound_ctrl:1
	ds_read_b128 v[32:35], v228 offset:29696
	ds_read_b128 v[36:39], v228 offset:33792
	v_add_f32_dpp v80, v80, v80 row_half_mirror row_mask:0xf bank_mask:0xf bound_ctrl:1
	ds_read_b128 v[40:43], v228 offset:37888
	ds_read_b32 v44, v229 offset:42240
	v_add_f32_dpp v80, v80, v80 row_mirror row_mask:0xf bank_mask:0xf bound_ctrl:1
	v_pk_fma_f32 v[52:53], v[64:65], v[80:81], v[78:79] op_sel_hi:[1,0,1] neg_lo:[0,1,0] neg_hi:[0,1,0]
	v_pk_fma_f32 v[50:51], v[62:63], v[80:81], v[76:77] op_sel_hi:[1,0,1] neg_lo:[0,1,0] neg_hi:[0,1,0]
	v_pk_mul_f32 v[82:83], v[72:73], v[52:53]
	s_nop 0
	v_pk_fma_f32 v[82:83], v[70:71], v[50:51], v[82:83]
	s_nop 0
	v_add_f32_e32 v82, v82, v83
	ds_write_b32 v246, v82 offset:512
	s_waitcnt lgkmcnt(8)
	v_pk_mul_f32 v[80:81], v[52:53], v[8:9]
	v_pk_mul_f32 v[76:77], v[14:15], v[22:23] op_sel_hi:[1,0]
	v_pk_fma_f32 v[80:81], v[50:51], v[6:7], v[80:81]
	v_pk_mul_f32 v[78:79], v[16:17], v[22:23] op_sel_hi:[1,0]
	v_add_f32_e32 v80, v80, v81
	v_pk_fma_f32 v[76:77], v[50:51], v[2:3], v[76:77]
	v_pk_fma_f32 v[78:79], v[52:53], v[4:5], v[78:79]
	v_add_f32_dpp v80, v80, v80 quad_perm:[1,0,3,2] row_mask:0xf bank_mask:0xf bound_ctrl:1
	ds_read_b128 v[54:57], v228 offset:21760
	ds_read_b128 v[58:61], v228 offset:25856
	v_add_f32_dpp v80, v80, v80 quad_perm:[2,3,0,1] row_mask:0xf bank_mask:0xf bound_ctrl:1
	ds_read_b128 v[62:65], v228 offset:29952
	ds_read_b128 v[66:69], v228 offset:34048
	v_add_f32_dpp v80, v80, v80 row_half_mirror row_mask:0xf bank_mask:0xf bound_ctrl:1
	ds_read_b128 v[70:73], v228 offset:38144
	ds_read_b32 v74, v229 offset:42304
	v_add_f32_dpp v80, v80, v80 row_mirror row_mask:0xf bank_mask:0xf bound_ctrl:1
	v_pk_fma_f32 v[52:53], v[12:13], v[80:81], v[78:79] op_sel_hi:[1,0,1] neg_lo:[0,1,0] neg_hi:[0,1,0]
	v_pk_fma_f32 v[50:51], v[10:11], v[80:81], v[76:77] op_sel_hi:[1,0,1] neg_lo:[0,1,0] neg_hi:[0,1,0]
	v_pk_mul_f32 v[82:83], v[20:21], v[52:53]
	s_nop 0
	v_pk_fma_f32 v[82:83], v[18:19], v[50:51], v[82:83]
	s_nop 0
	v_add_f32_e32 v82, v82, v83
	ds_write_b32 v246, v82 offset:768
	s_waitcnt lgkmcnt(8)
	v_pk_mul_f32 v[80:81], v[52:53], v[30:31]
	v_pk_mul_f32 v[76:77], v[36:37], v[44:45] op_sel_hi:[1,0]
	v_pk_fma_f32 v[80:81], v[50:51], v[28:29], v[80:81]
	v_pk_mul_f32 v[78:79], v[38:39], v[44:45] op_sel_hi:[1,0]
	v_add_f32_e32 v80, v80, v81
	v_pk_fma_f32 v[76:77], v[50:51], v[24:25], v[76:77]
	v_pk_fma_f32 v[78:79], v[52:53], v[26:27], v[78:79]
	v_add_f32_dpp v80, v80, v80 quad_perm:[1,0,3,2] row_mask:0xf bank_mask:0xf bound_ctrl:1
	ds_read_b128 v[2:5], v228 offset:22016
	ds_read_b128 v[6:9], v228 offset:26112
	v_add_f32_dpp v80, v80, v80 quad_perm:[2,3,0,1] row_mask:0xf bank_mask:0xf bound_ctrl:1
	ds_read_b128 v[10:13], v228 offset:30208
	ds_read_b128 v[14:17], v228 offset:34304
	v_add_f32_dpp v80, v80, v80 row_half_mirror row_mask:0xf bank_mask:0xf bound_ctrl:1
	ds_read_b128 v[18:21], v228 offset:38400
	ds_read_b32 v22, v229 offset:42368
	v_add_f32_dpp v80, v80, v80 row_mirror row_mask:0xf bank_mask:0xf bound_ctrl:1
	v_pk_fma_f32 v[52:53], v[34:35], v[80:81], v[78:79] op_sel_hi:[1,0,1] neg_lo:[0,1,0] neg_hi:[0,1,0]
	v_pk_fma_f32 v[50:51], v[32:33], v[80:81], v[76:77] op_sel_hi:[1,0,1] neg_lo:[0,1,0] neg_hi:[0,1,0]
	v_pk_mul_f32 v[82:83], v[42:43], v[52:53]
	s_nop 0
	v_pk_fma_f32 v[82:83], v[40:41], v[50:51], v[82:83]
	s_nop 0
	v_add_f32_e32 v82, v82, v83
	ds_write_b32 v246, v82 offset:1024
	s_waitcnt lgkmcnt(8)
	v_pk_mul_f32 v[80:81], v[52:53], v[60:61]
	v_pk_mul_f32 v[76:77], v[66:67], v[74:75] op_sel_hi:[1,0]
	v_pk_fma_f32 v[80:81], v[50:51], v[58:59], v[80:81]
	v_pk_mul_f32 v[78:79], v[68:69], v[74:75] op_sel_hi:[1,0]
	v_add_f32_e32 v80, v80, v81
	v_pk_fma_f32 v[76:77], v[50:51], v[54:55], v[76:77]
	v_pk_fma_f32 v[78:79], v[52:53], v[56:57], v[78:79]
	v_add_f32_dpp v80, v80, v80 quad_perm:[1,0,3,2] row_mask:0xf bank_mask:0xf bound_ctrl:1
	ds_read_b128 v[24:27], v228 offset:22272
	ds_read_b128 v[28:31], v228 offset:26368
	v_add_f32_dpp v80, v80, v80 quad_perm:[2,3,0,1] row_mask:0xf bank_mask:0xf bound_ctrl:1
	ds_read_b128 v[32:35], v228 offset:30464
	ds_read_b128 v[36:39], v228 offset:34560
	v_add_f32_dpp v80, v80, v80 row_half_mirror row_mask:0xf bank_mask:0xf bound_ctrl:1
	ds_read_b128 v[40:43], v228 offset:38656
	ds_read_b32 v44, v229 offset:42432
	v_add_f32_dpp v80, v80, v80 row_mirror row_mask:0xf bank_mask:0xf bound_ctrl:1
	v_pk_fma_f32 v[52:53], v[64:65], v[80:81], v[78:79] op_sel_hi:[1,0,1] neg_lo:[0,1,0] neg_hi:[0,1,0]
	v_pk_fma_f32 v[50:51], v[62:63], v[80:81], v[76:77] op_sel_hi:[1,0,1] neg_lo:[0,1,0] neg_hi:[0,1,0]
	v_pk_mul_f32 v[82:83], v[72:73], v[52:53]
	s_nop 0
	v_pk_fma_f32 v[82:83], v[70:71], v[50:51], v[82:83]
	s_nop 0
	v_add_f32_e32 v82, v82, v83
	ds_write_b32 v246, v82 offset:1280
	s_waitcnt lgkmcnt(8)
	v_pk_mul_f32 v[80:81], v[52:53], v[8:9]
	v_pk_mul_f32 v[76:77], v[14:15], v[22:23] op_sel_hi:[1,0]
	v_pk_fma_f32 v[80:81], v[50:51], v[6:7], v[80:81]
	v_pk_mul_f32 v[78:79], v[16:17], v[22:23] op_sel_hi:[1,0]
	v_add_f32_e32 v80, v80, v81
	v_pk_fma_f32 v[76:77], v[50:51], v[2:3], v[76:77]
	v_pk_fma_f32 v[78:79], v[52:53], v[4:5], v[78:79]
	v_add_f32_dpp v80, v80, v80 quad_perm:[1,0,3,2] row_mask:0xf bank_mask:0xf bound_ctrl:1
	ds_read_b128 v[54:57], v228 offset:22528
	ds_read_b128 v[58:61], v228 offset:26624
	v_add_f32_dpp v80, v80, v80 quad_perm:[2,3,0,1] row_mask:0xf bank_mask:0xf bound_ctrl:1
	ds_read_b128 v[62:65], v228 offset:30720
	ds_read_b128 v[66:69], v228 offset:34816
	v_add_f32_dpp v80, v80, v80 row_half_mirror row_mask:0xf bank_mask:0xf bound_ctrl:1
	ds_read_b128 v[70:73], v228 offset:38912
	ds_read_b32 v74, v229 offset:42496
	v_add_f32_dpp v80, v80, v80 row_mirror row_mask:0xf bank_mask:0xf bound_ctrl:1
	v_pk_fma_f32 v[52:53], v[12:13], v[80:81], v[78:79] op_sel_hi:[1,0,1] neg_lo:[0,1,0] neg_hi:[0,1,0]
	v_pk_fma_f32 v[50:51], v[10:11], v[80:81], v[76:77] op_sel_hi:[1,0,1] neg_lo:[0,1,0] neg_hi:[0,1,0]
	v_pk_mul_f32 v[82:83], v[20:21], v[52:53]
	s_nop 0
	v_pk_fma_f32 v[82:83], v[18:19], v[50:51], v[82:83]
	s_nop 0
	v_add_f32_e32 v82, v82, v83
	ds_write_b32 v246, v82 offset:1536
	s_waitcnt lgkmcnt(8)
	v_pk_mul_f32 v[80:81], v[52:53], v[30:31]
	v_pk_mul_f32 v[76:77], v[36:37], v[44:45] op_sel_hi:[1,0]
	v_pk_fma_f32 v[80:81], v[50:51], v[28:29], v[80:81]
	v_pk_mul_f32 v[78:79], v[38:39], v[44:45] op_sel_hi:[1,0]
	v_add_f32_e32 v80, v80, v81
	v_pk_fma_f32 v[76:77], v[50:51], v[24:25], v[76:77]
	v_pk_fma_f32 v[78:79], v[52:53], v[26:27], v[78:79]
	v_add_f32_dpp v80, v80, v80 quad_perm:[1,0,3,2] row_mask:0xf bank_mask:0xf bound_ctrl:1
	ds_read_b128 v[2:5], v228 offset:22784
	ds_read_b128 v[6:9], v228 offset:26880
	v_add_f32_dpp v80, v80, v80 quad_perm:[2,3,0,1] row_mask:0xf bank_mask:0xf bound_ctrl:1
	ds_read_b128 v[10:13], v228 offset:30976
	ds_read_b128 v[14:17], v228 offset:35072
	v_add_f32_dpp v80, v80, v80 row_half_mirror row_mask:0xf bank_mask:0xf bound_ctrl:1
	ds_read_b128 v[18:21], v228 offset:39168
	ds_read_b32 v22, v229 offset:42560
	v_add_f32_dpp v80, v80, v80 row_mirror row_mask:0xf bank_mask:0xf bound_ctrl:1
	v_pk_fma_f32 v[52:53], v[34:35], v[80:81], v[78:79] op_sel_hi:[1,0,1] neg_lo:[0,1,0] neg_hi:[0,1,0]
	v_pk_fma_f32 v[50:51], v[32:33], v[80:81], v[76:77] op_sel_hi:[1,0,1] neg_lo:[0,1,0] neg_hi:[0,1,0]
	v_pk_mul_f32 v[82:83], v[42:43], v[52:53]
	s_nop 0
	v_pk_fma_f32 v[82:83], v[40:41], v[50:51], v[82:83]
	s_nop 0
	v_add_f32_e32 v82, v82, v83
	ds_write_b32 v246, v82 offset:1792
	s_waitcnt lgkmcnt(8)
	v_pk_mul_f32 v[80:81], v[52:53], v[60:61]
	v_pk_mul_f32 v[76:77], v[66:67], v[74:75] op_sel_hi:[1,0]
	v_pk_fma_f32 v[80:81], v[50:51], v[58:59], v[80:81]
	v_pk_mul_f32 v[78:79], v[68:69], v[74:75] op_sel_hi:[1,0]
	v_add_f32_e32 v80, v80, v81
	v_pk_fma_f32 v[76:77], v[50:51], v[54:55], v[76:77]
	v_pk_fma_f32 v[78:79], v[52:53], v[56:57], v[78:79]
	v_add_f32_dpp v80, v80, v80 quad_perm:[1,0,3,2] row_mask:0xf bank_mask:0xf bound_ctrl:1
	ds_read_b128 v[24:27], v228 offset:23040
	ds_read_b128 v[28:31], v228 offset:27136
	v_add_f32_dpp v80, v80, v80 quad_perm:[2,3,0,1] row_mask:0xf bank_mask:0xf bound_ctrl:1
	ds_read_b128 v[32:35], v228 offset:31232
	ds_read_b128 v[36:39], v228 offset:35328
	v_add_f32_dpp v80, v80, v80 row_half_mirror row_mask:0xf bank_mask:0xf bound_ctrl:1
	ds_read_b128 v[40:43], v228 offset:39424
	ds_read_b32 v44, v229 offset:42624
	v_add_f32_dpp v80, v80, v80 row_mirror row_mask:0xf bank_mask:0xf bound_ctrl:1
	v_pk_fma_f32 v[52:53], v[64:65], v[80:81], v[78:79] op_sel_hi:[1,0,1] neg_lo:[0,1,0] neg_hi:[0,1,0]
	v_pk_fma_f32 v[50:51], v[62:63], v[80:81], v[76:77] op_sel_hi:[1,0,1] neg_lo:[0,1,0] neg_hi:[0,1,0]
	v_pk_mul_f32 v[82:83], v[72:73], v[52:53]
	s_nop 0
	v_pk_fma_f32 v[82:83], v[70:71], v[50:51], v[82:83]
	s_nop 0
	v_add_f32_e32 v82, v82, v83
	ds_write_b32 v246, v82 offset:2048
	s_waitcnt lgkmcnt(8)
	v_pk_mul_f32 v[80:81], v[52:53], v[8:9]
	v_pk_mul_f32 v[76:77], v[14:15], v[22:23] op_sel_hi:[1,0]
	v_pk_fma_f32 v[80:81], v[50:51], v[6:7], v[80:81]
	v_pk_mul_f32 v[78:79], v[16:17], v[22:23] op_sel_hi:[1,0]
	v_add_f32_e32 v80, v80, v81
	v_pk_fma_f32 v[76:77], v[50:51], v[2:3], v[76:77]
	v_pk_fma_f32 v[78:79], v[52:53], v[4:5], v[78:79]
	v_add_f32_dpp v80, v80, v80 quad_perm:[1,0,3,2] row_mask:0xf bank_mask:0xf bound_ctrl:1
	ds_read_b128 v[54:57], v228 offset:23296
	ds_read_b128 v[58:61], v228 offset:27392
	v_add_f32_dpp v80, v80, v80 quad_perm:[2,3,0,1] row_mask:0xf bank_mask:0xf bound_ctrl:1
	ds_read_b128 v[62:65], v228 offset:31488
	ds_read_b128 v[66:69], v228 offset:35584
	v_add_f32_dpp v80, v80, v80 row_half_mirror row_mask:0xf bank_mask:0xf bound_ctrl:1
	ds_read_b128 v[70:73], v228 offset:39680
	ds_read_b32 v74, v229 offset:42688
	v_add_f32_dpp v80, v80, v80 row_mirror row_mask:0xf bank_mask:0xf bound_ctrl:1
	v_pk_fma_f32 v[52:53], v[12:13], v[80:81], v[78:79] op_sel_hi:[1,0,1] neg_lo:[0,1,0] neg_hi:[0,1,0]
	v_pk_fma_f32 v[50:51], v[10:11], v[80:81], v[76:77] op_sel_hi:[1,0,1] neg_lo:[0,1,0] neg_hi:[0,1,0]
	v_pk_mul_f32 v[82:83], v[20:21], v[52:53]
	s_nop 0
	v_pk_fma_f32 v[82:83], v[18:19], v[50:51], v[82:83]
	s_nop 0
	v_add_f32_e32 v82, v82, v83
	ds_write_b32 v246, v82 offset:2304
	s_waitcnt lgkmcnt(8)
	v_pk_mul_f32 v[80:81], v[52:53], v[30:31]
	v_pk_mul_f32 v[76:77], v[36:37], v[44:45] op_sel_hi:[1,0]
	v_pk_fma_f32 v[80:81], v[50:51], v[28:29], v[80:81]
	v_pk_mul_f32 v[78:79], v[38:39], v[44:45] op_sel_hi:[1,0]
	v_add_f32_e32 v80, v80, v81
	v_pk_fma_f32 v[76:77], v[50:51], v[24:25], v[76:77]
	v_pk_fma_f32 v[78:79], v[52:53], v[26:27], v[78:79]
	v_add_f32_dpp v80, v80, v80 quad_perm:[1,0,3,2] row_mask:0xf bank_mask:0xf bound_ctrl:1
	ds_read_b128 v[2:5], v228 offset:23552
	ds_read_b128 v[6:9], v228 offset:27648
	v_add_f32_dpp v80, v80, v80 quad_perm:[2,3,0,1] row_mask:0xf bank_mask:0xf bound_ctrl:1
	ds_read_b128 v[10:13], v228 offset:31744
	ds_read_b128 v[14:17], v228 offset:35840
	v_add_f32_dpp v80, v80, v80 row_half_mirror row_mask:0xf bank_mask:0xf bound_ctrl:1
	ds_read_b128 v[18:21], v228 offset:39936
	ds_read_b32 v22, v229 offset:42752
	v_add_f32_dpp v80, v80, v80 row_mirror row_mask:0xf bank_mask:0xf bound_ctrl:1
	v_pk_fma_f32 v[52:53], v[34:35], v[80:81], v[78:79] op_sel_hi:[1,0,1] neg_lo:[0,1,0] neg_hi:[0,1,0]
	v_pk_fma_f32 v[50:51], v[32:33], v[80:81], v[76:77] op_sel_hi:[1,0,1] neg_lo:[0,1,0] neg_hi:[0,1,0]
	v_pk_mul_f32 v[82:83], v[42:43], v[52:53]
	s_nop 0
	v_pk_fma_f32 v[82:83], v[40:41], v[50:51], v[82:83]
	s_nop 0
	v_add_f32_e32 v82, v82, v83
	ds_write_b32 v246, v82 offset:2560
	s_waitcnt lgkmcnt(8)
	v_pk_mul_f32 v[80:81], v[52:53], v[60:61]
	v_pk_mul_f32 v[76:77], v[66:67], v[74:75] op_sel_hi:[1,0]
	v_pk_fma_f32 v[80:81], v[50:51], v[58:59], v[80:81]
	v_pk_mul_f32 v[78:79], v[68:69], v[74:75] op_sel_hi:[1,0]
	v_add_f32_e32 v80, v80, v81
	v_pk_fma_f32 v[76:77], v[50:51], v[54:55], v[76:77]
	v_pk_fma_f32 v[78:79], v[52:53], v[56:57], v[78:79]
	v_add_f32_dpp v80, v80, v80 quad_perm:[1,0,3,2] row_mask:0xf bank_mask:0xf bound_ctrl:1
	ds_read_b128 v[24:27], v228 offset:23808
	ds_read_b128 v[28:31], v228 offset:27904
	v_add_f32_dpp v80, v80, v80 quad_perm:[2,3,0,1] row_mask:0xf bank_mask:0xf bound_ctrl:1
	ds_read_b128 v[32:35], v228 offset:32000
	ds_read_b128 v[36:39], v228 offset:36096
	v_add_f32_dpp v80, v80, v80 row_half_mirror row_mask:0xf bank_mask:0xf bound_ctrl:1
	ds_read_b128 v[40:43], v228 offset:40192
	ds_read_b32 v44, v229 offset:42816
	v_add_f32_dpp v80, v80, v80 row_mirror row_mask:0xf bank_mask:0xf bound_ctrl:1
	v_pk_fma_f32 v[52:53], v[64:65], v[80:81], v[78:79] op_sel_hi:[1,0,1] neg_lo:[0,1,0] neg_hi:[0,1,0]
	v_pk_fma_f32 v[50:51], v[62:63], v[80:81], v[76:77] op_sel_hi:[1,0,1] neg_lo:[0,1,0] neg_hi:[0,1,0]
	v_pk_mul_f32 v[82:83], v[72:73], v[52:53]
	s_nop 0
	v_pk_fma_f32 v[82:83], v[70:71], v[50:51], v[82:83]
	s_nop 0
	v_add_f32_e32 v82, v82, v83
	ds_write_b32 v246, v82 offset:2816
	s_waitcnt lgkmcnt(8)
	v_pk_mul_f32 v[80:81], v[52:53], v[8:9]
	v_pk_mul_f32 v[76:77], v[14:15], v[22:23] op_sel_hi:[1,0]
	v_pk_fma_f32 v[80:81], v[50:51], v[6:7], v[80:81]
	v_pk_mul_f32 v[78:79], v[16:17], v[22:23] op_sel_hi:[1,0]
	v_add_f32_e32 v80, v80, v81
	v_pk_fma_f32 v[76:77], v[50:51], v[2:3], v[76:77]
	v_pk_fma_f32 v[78:79], v[52:53], v[4:5], v[78:79]
	v_add_f32_dpp v80, v80, v80 quad_perm:[1,0,3,2] row_mask:0xf bank_mask:0xf bound_ctrl:1
	ds_read_b128 v[54:57], v228 offset:24064
	ds_read_b128 v[58:61], v228 offset:28160
	v_add_f32_dpp v80, v80, v80 quad_perm:[2,3,0,1] row_mask:0xf bank_mask:0xf bound_ctrl:1
	ds_read_b128 v[62:65], v228 offset:32256
	ds_read_b128 v[66:69], v228 offset:36352
	v_add_f32_dpp v80, v80, v80 row_half_mirror row_mask:0xf bank_mask:0xf bound_ctrl:1
	ds_read_b128 v[70:73], v228 offset:40448
	ds_read_b32 v74, v229 offset:42880
	v_add_f32_dpp v80, v80, v80 row_mirror row_mask:0xf bank_mask:0xf bound_ctrl:1
	v_pk_fma_f32 v[52:53], v[12:13], v[80:81], v[78:79] op_sel_hi:[1,0,1] neg_lo:[0,1,0] neg_hi:[0,1,0]
	v_pk_fma_f32 v[50:51], v[10:11], v[80:81], v[76:77] op_sel_hi:[1,0,1] neg_lo:[0,1,0] neg_hi:[0,1,0]
	v_pk_mul_f32 v[82:83], v[20:21], v[52:53]
	s_nop 0
	v_pk_fma_f32 v[82:83], v[18:19], v[50:51], v[82:83]
	s_nop 0
	v_add_f32_e32 v82, v82, v83
	ds_write_b32 v246, v82 offset:3072
	s_waitcnt lgkmcnt(8)
	v_pk_mul_f32 v[80:81], v[52:53], v[30:31]
	v_pk_mul_f32 v[76:77], v[36:37], v[44:45] op_sel_hi:[1,0]
	v_pk_fma_f32 v[80:81], v[50:51], v[28:29], v[80:81]
	v_pk_mul_f32 v[78:79], v[38:39], v[44:45] op_sel_hi:[1,0]
	v_add_f32_e32 v80, v80, v81
	v_pk_fma_f32 v[76:77], v[50:51], v[24:25], v[76:77]
	v_pk_fma_f32 v[78:79], v[52:53], v[26:27], v[78:79]
	v_add_f32_dpp v80, v80, v80 quad_perm:[1,0,3,2] row_mask:0xf bank_mask:0xf bound_ctrl:1
	ds_read_b128 v[2:5], v228 offset:24320
	ds_read_b128 v[6:9], v228 offset:28416
	v_add_f32_dpp v80, v80, v80 quad_perm:[2,3,0,1] row_mask:0xf bank_mask:0xf bound_ctrl:1
	ds_read_b128 v[10:13], v228 offset:32512
	ds_read_b128 v[14:17], v228 offset:36608
	v_add_f32_dpp v80, v80, v80 row_half_mirror row_mask:0xf bank_mask:0xf bound_ctrl:1
	ds_read_b128 v[18:21], v228 offset:40704
	ds_read_b32 v22, v229 offset:42944
	v_add_f32_dpp v80, v80, v80 row_mirror row_mask:0xf bank_mask:0xf bound_ctrl:1
	v_pk_fma_f32 v[52:53], v[34:35], v[80:81], v[78:79] op_sel_hi:[1,0,1] neg_lo:[0,1,0] neg_hi:[0,1,0]
	v_pk_fma_f32 v[50:51], v[32:33], v[80:81], v[76:77] op_sel_hi:[1,0,1] neg_lo:[0,1,0] neg_hi:[0,1,0]
	v_pk_mul_f32 v[82:83], v[42:43], v[52:53]
	s_nop 0
	v_pk_fma_f32 v[82:83], v[40:41], v[50:51], v[82:83]
	s_nop 0
	v_add_f32_e32 v82, v82, v83
	ds_write_b32 v246, v82 offset:3328
	s_waitcnt lgkmcnt(8)
	v_pk_mul_f32 v[80:81], v[52:53], v[60:61]
	v_pk_mul_f32 v[76:77], v[66:67], v[74:75] op_sel_hi:[1,0]
	v_pk_fma_f32 v[80:81], v[50:51], v[58:59], v[80:81]
	v_pk_mul_f32 v[78:79], v[68:69], v[74:75] op_sel_hi:[1,0]
	v_add_f32_e32 v80, v80, v81
	v_pk_fma_f32 v[76:77], v[50:51], v[54:55], v[76:77]
	v_pk_fma_f32 v[78:79], v[52:53], v[56:57], v[78:79]
	v_add_f32_dpp v80, v80, v80 quad_perm:[1,0,3,2] row_mask:0xf bank_mask:0xf bound_ctrl:1
	s_nop 1
	v_add_f32_dpp v80, v80, v80 quad_perm:[2,3,0,1] row_mask:0xf bank_mask:0xf bound_ctrl:1
	s_nop 1
	v_add_f32_dpp v80, v80, v80 row_half_mirror row_mask:0xf bank_mask:0xf bound_ctrl:1
	s_nop 1
	v_add_f32_dpp v80, v80, v80 row_mirror row_mask:0xf bank_mask:0xf bound_ctrl:1
	v_pk_fma_f32 v[52:53], v[64:65], v[80:81], v[78:79] op_sel_hi:[1,0,1] neg_lo:[0,1,0] neg_hi:[0,1,0]
	v_pk_fma_f32 v[50:51], v[62:63], v[80:81], v[76:77] op_sel_hi:[1,0,1] neg_lo:[0,1,0] neg_hi:[0,1,0]
	v_pk_mul_f32 v[82:83], v[72:73], v[52:53]
	s_nop 0
	v_pk_fma_f32 v[82:83], v[70:71], v[50:51], v[82:83]
	s_nop 0
	v_add_f32_e32 v82, v82, v83
	ds_write_b32 v246, v82 offset:3584
	s_waitcnt lgkmcnt(2)
	v_pk_mul_f32 v[80:81], v[52:53], v[8:9]
	v_pk_mul_f32 v[76:77], v[14:15], v[22:23] op_sel_hi:[1,0]
	v_pk_fma_f32 v[80:81], v[50:51], v[6:7], v[80:81]
	v_pk_mul_f32 v[78:79], v[16:17], v[22:23] op_sel_hi:[1,0]
	v_add_f32_e32 v80, v80, v81
	v_pk_fma_f32 v[76:77], v[50:51], v[2:3], v[76:77]
	v_pk_fma_f32 v[78:79], v[52:53], v[4:5], v[78:79]
	v_add_f32_dpp v80, v80, v80 quad_perm:[1,0,3,2] row_mask:0xf bank_mask:0xf bound_ctrl:1
	s_nop 1
	v_add_f32_dpp v80, v80, v80 quad_perm:[2,3,0,1] row_mask:0xf bank_mask:0xf bound_ctrl:1
	s_nop 1
	v_add_f32_dpp v80, v80, v80 row_half_mirror row_mask:0xf bank_mask:0xf bound_ctrl:1
	s_nop 1
	v_add_f32_dpp v80, v80, v80 row_mirror row_mask:0xf bank_mask:0xf bound_ctrl:1
	v_pk_fma_f32 v[52:53], v[12:13], v[80:81], v[78:79] op_sel_hi:[1,0,1] neg_lo:[0,1,0] neg_hi:[0,1,0]
	v_pk_fma_f32 v[50:51], v[10:11], v[80:81], v[76:77] op_sel_hi:[1,0,1] neg_lo:[0,1,0] neg_hi:[0,1,0]
	v_pk_mul_f32 v[82:83], v[20:21], v[52:53]
	s_nop 0
	v_pk_fma_f32 v[82:83], v[18:19], v[50:51], v[82:83]
	s_nop 0
	v_add_f32_e32 v82, v82, v83
	ds_write_b32 v246, v82 offset:3840
	s_setprio 0
